# v20 + Hyena gating stages: the 8-16 serial own-slot LDS reads per stage issued together (8 in flight) with renamed uses and counted waits
# speedup vs baseline: 1.0124x; 1.0124x over previous
.LBB0_448:
	s_or_b64 exec, exec, s[0:1]
	v_mov_b32_e32 v102, 0
	v_mov_b32_e32 v110, 0
	v_mov_b32_e32 v111, 0
	s_and_saveexec_b64 s[0:1], s[42:43]
	s_cbranch_execz .LBB0_450
	ds_read_b64 v[182:183], v152
	ds_read_b64 v[184:185], v152 offset:8
	ds_read_b64 v[186:187], v152 offset:16
	ds_read_b64 v[188:189], v152 offset:24
	ds_read_b64 v[190:191], v152 offset:32
	ds_read_b64 v[192:193], v152 offset:40
	ds_read_b64 v[194:195], v152 offset:48
	ds_read_b64 v[196:197], v152 offset:56
	s_waitcnt lgkmcnt(7)
	v_pk_fma_f32 v[2:3], v[46:47], v[94:95], v[182:183]
	v_pk_fma_f32 v[0:1], v[46:47], v[94:95], v[182:183] op_sel_hi:[0,1,1] neg_lo:[0,0,1] neg_hi:[0,0,1]
	v_mov_b32_e32 v3, v1
	v_pk_mul_f32 v[110:111], v[124:125], v[2:3]
.LBB0_450:
	s_or_b64 exec, exec, s[0:1]
	v_mov_b32_e32 v103, 0
	s_and_saveexec_b64 s[0:1], s[42:43]
	s_cbranch_execz .LBB0_452
	s_waitcnt lgkmcnt(6)
	v_pk_fma_f32 v[2:3], v[46:47], v[88:89], v[184:185]
	v_pk_fma_f32 v[0:1], v[46:47], v[88:89], v[184:185] op_sel_hi:[0,1,1] neg_lo:[0,0,1] neg_hi:[0,0,1]
	v_mov_b32_e32 v3, v1
	v_pk_mul_f32 v[102:103], v[122:123], v[2:3]
.LBB0_452:
	s_or_b64 exec, exec, s[0:1]
	v_mov_b32_e32 v88, 0
	v_mov_b32_e32 v94, 0
	v_mov_b32_e32 v95, 0
	s_and_saveexec_b64 s[0:1], s[42:43]
	s_cbranch_execz .LBB0_454
	s_waitcnt lgkmcnt(5)
	v_pk_fma_f32 v[2:3], v[46:47], v[112:113], v[186:187]
	v_pk_fma_f32 v[0:1], v[46:47], v[112:113], v[186:187] op_sel_hi:[0,1,1] neg_lo:[0,0,1] neg_hi:[0,0,1]
	v_mov_b32_e32 v3, v1
	v_pk_mul_f32 v[94:95], v[120:121], v[2:3]
.LBB0_454:
	s_or_b64 exec, exec, s[0:1]
	v_mov_b32_e32 v89, 0
	s_and_saveexec_b64 s[0:1], s[42:43]
	s_cbranch_execz .LBB0_456
	s_waitcnt lgkmcnt(4)
	v_pk_fma_f32 v[2:3], v[46:47], v[104:105], v[188:189]
	v_pk_fma_f32 v[0:1], v[46:47], v[104:105], v[188:189] op_sel_hi:[0,1,1] neg_lo:[0,0,1] neg_hi:[0,0,1]
	v_mov_b32_e32 v3, v1
	v_pk_mul_f32 v[88:89], v[118:119], v[2:3]
.LBB0_456:
	s_or_b64 exec, exec, s[0:1]
	v_mov_b32_e32 v104, 0
	v_mov_b32_e32 v112, 0
	v_mov_b32_e32 v113, 0
	s_and_saveexec_b64 s[0:1], s[42:43]
	s_cbranch_execz .LBB0_458
	s_waitcnt lgkmcnt(3)
	v_pk_fma_f32 v[2:3], v[46:47], v[96:97], v[190:191]
	v_pk_fma_f32 v[0:1], v[46:47], v[96:97], v[190:191] op_sel_hi:[0,1,1] neg_lo:[0,0,1] neg_hi:[0,0,1]
	v_mov_b32_e32 v3, v1
	v_pk_mul_f32 v[112:113], v[30:31], v[2:3]
.LBB0_458:
	s_or_b64 exec, exec, s[0:1]
	v_mov_b32_e32 v105, 0
	s_and_saveexec_b64 s[0:1], s[42:43]
	s_cbranch_execz .LBB0_460
	s_waitcnt lgkmcnt(2)
	v_pk_fma_f32 v[2:3], v[46:47], v[90:91], v[192:193]
	v_pk_fma_f32 v[0:1], v[46:47], v[90:91], v[192:193] op_sel_hi:[0,1,1] neg_lo:[0,0,1] neg_hi:[0,0,1]
	v_mov_b32_e32 v3, v1
	v_pk_mul_f32 v[104:105], v[28:29], v[2:3]
.LBB0_460:
	s_or_b64 exec, exec, s[0:1]
	v_mov_b32_e32 v90, 0
	v_mov_b32_e32 v96, 0
	v_mov_b32_e32 v97, 0
	s_and_saveexec_b64 s[0:1], s[42:43]
	s_cbranch_execz .LBB0_462
	s_waitcnt lgkmcnt(1)
	v_pk_fma_f32 v[2:3], v[46:47], v[114:115], v[194:195]
	v_pk_fma_f32 v[0:1], v[46:47], v[114:115], v[194:195] op_sel_hi:[0,1,1] neg_lo:[0,0,1] neg_hi:[0,0,1]
	v_mov_b32_e32 v3, v1
	v_pk_mul_f32 v[96:97], v[26:27], v[2:3]
.LBB0_462:
	s_or_b64 exec, exec, s[0:1]
	v_mov_b32_e32 v91, 0
	s_and_saveexec_b64 s[0:1], s[42:43]
	s_cbranch_execz .LBB0_464
	s_waitcnt lgkmcnt(0)
	v_pk_fma_f32 v[2:3], v[46:47], v[106:107], v[196:197]
	v_pk_fma_f32 v[0:1], v[46:47], v[106:107], v[196:197] op_sel_hi:[0,1,1] neg_lo:[0,0,1] neg_hi:[0,0,1]
	v_mov_b32_e32 v3, v1
	v_pk_mul_f32 v[90:91], v[24:25], v[2:3]
.LBB0_464:
	s_or_b64 exec, exec, s[0:1]
	v_mov_b32_e32 v106, 0
	v_mov_b32_e32 v114, 0
	v_mov_b32_e32 v115, 0
	s_and_saveexec_b64 s[0:1], s[42:43]
	s_cbranch_execz .LBB0_466
	ds_read_b64 v[198:199], v152 offset:64
	ds_read_b64 v[200:201], v152 offset:72
	ds_read_b64 v[202:203], v152 offset:80
	ds_read_b64 v[214:215], v152 offset:88
	ds_read_b64 v[216:217], v152 offset:96
	ds_read_b64 v[218:219], v152 offset:104
	ds_read_b64 v[220:221], v152 offset:112
	ds_read_b64 v[222:223], v152 offset:120
	s_waitcnt lgkmcnt(7)
	v_pk_fma_f32 v[2:3], v[46:47], v[98:99], v[198:199]
	v_pk_fma_f32 v[0:1], v[46:47], v[98:99], v[198:199] op_sel_hi:[0,1,1] neg_lo:[0,0,1] neg_hi:[0,0,1]
	v_mov_b32_e32 v3, v1
	v_pk_mul_f32 v[114:115], v[22:23], v[2:3]
.LBB0_466:
	s_or_b64 exec, exec, s[0:1]
	v_mov_b32_e32 v107, 0
	s_and_saveexec_b64 s[0:1], s[42:43]
	s_cbranch_execz .LBB0_468
	s_waitcnt lgkmcnt(6)
	v_pk_fma_f32 v[2:3], v[46:47], v[92:93], v[200:201]
	v_pk_fma_f32 v[0:1], v[46:47], v[92:93], v[200:201] op_sel_hi:[0,1,1] neg_lo:[0,0,1] neg_hi:[0,0,1]
	v_mov_b32_e32 v3, v1
	v_pk_mul_f32 v[106:107], v[20:21], v[2:3]
.LBB0_468:
	s_or_b64 exec, exec, s[0:1]
	v_mov_b32_e32 v92, 0
	v_mov_b32_e32 v98, 0
	v_mov_b32_e32 v99, 0
	s_and_saveexec_b64 s[0:1], s[42:43]
	s_cbranch_execz .LBB0_470
	s_waitcnt lgkmcnt(5)
	v_pk_fma_f32 v[2:3], v[46:47], v[116:117], v[202:203]
	v_pk_fma_f32 v[0:1], v[46:47], v[116:117], v[202:203] op_sel_hi:[0,1,1] neg_lo:[0,0,1] neg_hi:[0,0,1]
	v_mov_b32_e32 v3, v1
	v_pk_mul_f32 v[98:99], v[18:19], v[2:3]
.LBB0_470:
	s_or_b64 exec, exec, s[0:1]
	v_mov_b32_e32 v93, 0
	s_and_saveexec_b64 s[0:1], s[42:43]
	s_cbranch_execz .LBB0_472
	s_waitcnt lgkmcnt(4)
	v_pk_fma_f32 v[2:3], v[46:47], v[108:109], v[214:215]
	v_pk_fma_f32 v[0:1], v[46:47], v[108:109], v[214:215] op_sel_hi:[0,1,1] neg_lo:[0,0,1] neg_hi:[0,0,1]
	v_mov_b32_e32 v3, v1
	v_pk_mul_f32 v[92:93], v[16:17], v[2:3]
.LBB0_472:
	s_or_b64 exec, exec, s[0:1]
	v_mov_b32_e32 v108, 0
	v_mov_b32_e32 v116, 0
	v_mov_b32_e32 v117, 0
	s_and_saveexec_b64 s[0:1], s[42:43]
	s_cbranch_execz .LBB0_474
	s_waitcnt lgkmcnt(3)
	v_pk_fma_f32 v[2:3], v[46:47], v[100:101], v[216:217]
	v_pk_fma_f32 v[0:1], v[46:47], v[100:101], v[216:217] op_sel_hi:[0,1,1] neg_lo:[0,0,1] neg_hi:[0,0,1]
	v_mov_b32_e32 v3, v1
	v_pk_mul_f32 v[116:117], v[14:15], v[2:3]
.LBB0_474:
	s_or_b64 exec, exec, s[0:1]
	v_mov_b32_e32 v109, 0
	s_and_saveexec_b64 s[0:1], s[42:43]
	s_cbranch_execz .LBB0_476
	s_waitcnt lgkmcnt(2)
	v_pk_fma_f32 v[2:3], v[46:47], v[86:87], v[218:219]
	v_pk_fma_f32 v[0:1], v[46:47], v[86:87], v[218:219] op_sel_hi:[0,1,1] neg_lo:[0,0,1] neg_hi:[0,0,1]
	v_mov_b32_e32 v3, v1
	v_pk_mul_f32 v[108:109], v[12:13], v[2:3]
.LBB0_476:
	s_or_b64 exec, exec, s[0:1]
	v_mov_b32_e32 v86, 0
	v_mov_b32_e32 v100, 0
	v_mov_b32_e32 v101, 0
	s_and_saveexec_b64 s[0:1], s[42:43]
	s_cbranch_execz .LBB0_478
	s_waitcnt lgkmcnt(1)
	v_pk_fma_f32 v[2:3], v[46:47], v[84:85], v[220:221]
	v_pk_fma_f32 v[0:1], v[46:47], v[84:85], v[220:221] op_sel_hi:[0,1,1] neg_lo:[0,0,1] neg_hi:[0,0,1]
	v_mov_b32_e32 v3, v1
	v_pk_mul_f32 v[100:101], v[10:11], v[2:3]
.LBB0_478:
	s_or_b64 exec, exec, s[0:1]
	v_mov_b32_e32 v87, 0
	s_and_saveexec_b64 s[0:1], s[42:43]
	s_cbranch_execz .LBB0_480
	s_waitcnt lgkmcnt(0)
	v_pk_fma_f32 v[2:3], v[46:47], v[82:83], v[222:223]
	v_pk_fma_f32 v[0:1], v[46:47], v[82:83], v[222:223] op_sel_hi:[0,1,1] neg_lo:[0,0,1] neg_hi:[0,0,1]
	v_mov_b32_e32 v3, v1
	v_pk_mul_f32 v[86:87], v[8:9], v[2:3]

.LBB0_499:
	s_or_b64 exec, exec, s[4:5]
	s_waitcnt vmcnt(0)
	v_lshlrev_b32_e32 v21, 16, v33
	v_lshlrev_b32_e32 v19, 16, v37
	v_lshlrev_b32_e32 v20, 16, v47
	v_lshlrev_b32_e32 v18, 16, v80
	v_lshlrev_b32_e32 v16, 16, v12
	v_fma_f32 v21, v148, v21, v149
	v_and_b32_e32 v12, 0xffff0000, v12
	v_fmac_f32_e32 v21, v45, v16
	v_fma_f32 v16, v148, v16, v149
	v_lshlrev_b32_e32 v17, 16, v13
	v_fmac_f32_e32 v16, v45, v12
	v_fma_f32 v28, v148, v12, v149
	v_and_b32_e32 v13, 0xffff0000, v13
	v_fmac_f32_e32 v16, v44, v17
	v_fmac_f32_e32 v28, v45, v17
	v_fma_f32 v17, v148, v17, v149
	v_lshlrev_b32_e32 v22, 16, v14
	v_fmac_f32_e32 v17, v45, v13
	v_fma_f32 v29, v148, v13, v149
	v_and_b32_e32 v14, 0xffff0000, v14
	v_fmac_f32_e32 v17, v44, v22
	v_fmac_f32_e32 v29, v45, v22
	v_fma_f32 v22, v148, v22, v149
	v_lshlrev_b32_e32 v23, 16, v15
	v_fmac_f32_e32 v22, v45, v14
	v_fma_f32 v30, v148, v14, v149
	v_and_b32_e32 v15, 0xffff0000, v15
	v_fmac_f32_e32 v22, v44, v23
	v_fmac_f32_e32 v30, v45, v23
	v_fma_f32 v23, v148, v23, v149
	s_waitcnt vmcnt(2)
	v_lshlrev_b32_e32 v24, 16, v8
	v_fmac_f32_e32 v23, v45, v15
	v_fma_f32 v31, v148, v15, v149
	v_and_b32_e32 v8, 0xffff0000, v8
	v_fmac_f32_e32 v23, v44, v24
	v_fmac_f32_e32 v31, v45, v24
	v_fma_f32 v24, v148, v24, v149
	v_lshlrev_b32_e32 v25, 16, v9
	v_fmac_f32_e32 v24, v45, v8
	v_fma_f32 v37, v148, v8, v149
	v_and_b32_e32 v9, 0xffff0000, v9
	v_fmac_f32_e32 v24, v44, v25
	v_fmac_f32_e32 v37, v45, v25
	v_fma_f32 v25, v148, v25, v149
	v_lshlrev_b32_e32 v26, 16, v10
	v_fmac_f32_e32 v25, v45, v9
	v_fma_f32 v39, v148, v9, v149
	v_and_b32_e32 v10, 0xffff0000, v10
	v_lshlrev_b32_e32 v27, 16, v11
	v_fmac_f32_e32 v25, v44, v26
	v_fmac_f32_e32 v39, v45, v26
	v_fma_f32 v26, v148, v26, v149
	v_and_b32_e32 v11, 0xffff0000, v11
	v_fmac_f32_e32 v31, v44, v8
	v_fmac_f32_e32 v37, v44, v9
	v_fmac_f32_e32 v39, v44, v10
	v_fmac_f32_e32 v26, v45, v10
	v_fma_f32 v8, v148, v10, v149
	v_fma_f32 v9, v148, v27, v149
	s_waitcnt vmcnt(1)
	v_and_b32_e32 v10, 0xffff0000, v4
	v_fmac_f32_e32 v21, v44, v12
	v_fmac_f32_e32 v28, v44, v13
	v_fmac_f32_e32 v9, v45, v11
	v_lshlrev_b32_e32 v13, 16, v4
	v_mov_b32_e32 v12, v10
	v_fmac_f32_e32 v29, v44, v14
	v_fmac_f32_e32 v30, v44, v15
	v_fmac_f32_e32 v8, v45, v27
	v_fmac_f32_e32 v9, v44, v19
	v_fma_f32 v19, v148, v20, v149
	v_pk_mul_f32 v[14:15], v[44:45], v[12:13]
	v_fmac_f32_e32 v8, v44, v11
	v_and_b32_e32 v11, 16, v4
	v_add_f32_e32 v4, v15, v19
	v_and_b32_e32 v12, 0xffff0000, v5
	v_add_f32_e32 v14, v14, v4
	v_fma_f32 v15, v148, v13, v149
	v_and_b32_e32 v13, 16, v5
	v_lshlrev_b32_e32 v5, 16, v5
	v_mov_b32_e32 v4, v12
	v_fma_f32 v19, v148, v10, v149
	v_pk_mov_b32 v[10:11], v[4:5], v[10:11] op_sel:[1,0]
	v_fmac_f32_e32 v26, v44, v27
	v_pk_mul_f32 v[10:11], v[44:45], v[10:11]
	v_fma_f32 v27, v148, v12, v149
	v_add_f32_e32 v11, v11, v15
	v_add_f32_e32 v15, v10, v11
	v_pk_mul_f32 v[10:11], v[44:45], v[4:5]
	v_fma_f32 v20, v148, v5, v149
	v_add_f32_e32 v4, v11, v19
	v_add_f32_e32 v19, v10, v4
	v_and_b32_e32 v4, 0xffff0000, v6
	v_lshlrev_b32_e32 v11, 16, v6
	v_mov_b32_e32 v10, v4
	v_pk_mov_b32 v[12:13], v[10:11], v[12:13] op_sel:[1,0]
	v_and_b32_e32 v5, 16, v6
	v_pk_mul_f32 v[12:13], v[44:45], v[12:13]
	s_mov_b64 s[4:5], 0xc0000
	v_add_f32_e32 v6, v13, v20
	v_add_f32_e32 v20, v12, v6
	v_pk_mul_f32 v[12:13], v[44:45], v[10:11]
	v_and_b32_e32 v10, 0xffff0000, v7
	v_add_f32_e32 v6, v13, v27
	v_add_f32_e32 v12, v12, v6
	v_fma_f32 v13, v148, v11, v149
	v_and_b32_e32 v11, 16, v7
	v_lshlrev_b32_e32 v7, 16, v7
	v_mov_b32_e32 v6, v10
	v_fma_f32 v27, v148, v4, v149
	v_pk_mov_b32 v[4:5], v[6:7], v[4:5] op_sel:[1,0]
	v_fma_f32 v47, v148, v7, v149
	v_pk_mul_f32 v[4:5], v[44:45], v[4:5]
	v_fma_f32 v81, v148, v10, v149
	v_add_f32_e32 v5, v5, v13
	v_add_f32_e32 v13, v4, v5
	v_pk_mul_f32 v[4:5], v[44:45], v[6:7]
	s_waitcnt vmcnt(0)
	v_lshlrev_b32_e32 v7, 16, v0
	v_add_f32_e32 v5, v5, v27
	v_add_f32_e32 v27, v4, v5
	v_and_b32_e32 v4, 0xffff0000, v0
	v_mov_b32_e32 v6, v4
	v_pk_mov_b32 v[10:11], v[6:7], v[10:11] op_sel:[1,0]
	v_and_b32_e32 v5, 16, v0
	v_pk_mul_f32 v[10:11], v[44:45], v[10:11]
	s_nop 0
	v_add_f32_e32 v0, v11, v47
	v_add_f32_e32 v47, v10, v0
	v_pk_mul_f32 v[10:11], v[44:45], v[6:7]
	v_and_b32_e32 v6, 0xffff0000, v1
	v_add_f32_e32 v0, v81, v11
	v_add_f32_e32 v10, v10, v0
	v_fma_f32 v11, v148, v7, v149
	v_and_b32_e32 v7, 16, v1
	v_lshlrev_b32_e32 v1, 16, v1
	v_mov_b32_e32 v0, v6
	v_fma_f32 v81, v148, v4, v149
	v_pk_mov_b32 v[4:5], v[0:1], v[4:5] op_sel:[1,0]
	v_fma_f32 v83, v148, v6, v149
	v_pk_mul_f32 v[4:5], v[44:45], v[4:5]
	v_fma_f32 v82, v148, v1, v149
	v_add_f32_e32 v5, v5, v11
	v_add_f32_e32 v11, v4, v5
	v_pk_mul_f32 v[4:5], v[44:45], v[0:1]
	v_and_b32_e32 v1, 16, v2
	v_add_f32_e32 v0, v5, v81
	v_add_f32_e32 v81, v4, v0
	v_and_b32_e32 v0, 0xffff0000, v2
	v_lshlrev_b32_e32 v5, 16, v2
	v_mov_b32_e32 v4, v0
	v_pk_mov_b32 v[6:7], v[4:5], v[6:7] op_sel:[1,0]
	s_nop 0
	v_pk_mul_f32 v[6:7], v[44:45], v[6:7]
	s_nop 0
	v_add_f32_e32 v2, v7, v82
	v_add_f32_e32 v82, v6, v2
	v_pk_mul_f32 v[6:7], v[44:45], v[4:5]
	v_fma_f32 v5, v148, v5, v149
	v_add_f32_e32 v2, v7, v83
	v_add_f32_e32 v4, v6, v2
	v_and_b32_e32 v2, 0xffff0000, v3
	v_lshlrev_b32_e32 v3, 16, v3
	v_fma_f32 v6, v148, v0, v149
	v_pk_mov_b32 v[0:1], v[2:3], v[0:1] op_sel:[1,0]
	v_fma_f32 v7, v148, v3, v149
	v_pk_mul_f32 v[0:1], v[44:45], v[0:1]
	s_nop 0
	v_add_f32_e32 v1, v1, v5
	v_add_f32_e32 v5, v0, v1
	v_pk_mul_f32 v[0:1], v[44:45], v[2:3]
	v_mov_b32_e32 v3, v18
	v_add_f32_e32 v1, v1, v6
	v_add_f32_e32 v6, v0, v1
	v_mov_b32_e32 v0, v45
	v_mov_b32_e32 v1, v44
	v_pk_mul_f32 v[0:1], v[0:1], v[2:3]
	s_nop 0
	v_add_f32_e32 v0, v0, v7
	v_add_f32_e32 v7, v0, v1
	ds_read2_b64 v[182:185], v152 offset1:1
	ds_read2_b64 v[186:189], v152 offset0:2 offset1:3
	ds_read2_b64 v[190:193], v152 offset0:4 offset1:5
	ds_read2_b64 v[194:197], v152 offset0:6 offset1:7
	ds_read2_b64 v[198:201], v152 offset0:8 offset1:9
	ds_read2_b64 v[214:217], v152 offset0:10 offset1:11
	ds_read2_b64 v[218:221], v152 offset0:12 offset1:13
	ds_read2_b64 v[222:225], v152 offset0:14 offset1:15
	s_waitcnt lgkmcnt(7)
	v_fma_f32 v0, v150, v110, v182
	v_mul_f32_e32 v18, v21, v0
	v_fma_f32 v0, v150, v111, -v183
	v_mul_f32_e32 v14, v14, v0
	v_fma_f32 v0, v150, v102, v184
	v_mul_f32_e32 v16, v16, v0
	v_fma_f32 v0, v150, v103, -v185
	v_mul_f32_e32 v15, v15, v0
	s_waitcnt lgkmcnt(6)
	v_fma_f32 v0, v150, v94, v186
	v_mul_f32_e32 v21, v28, v0
	v_fma_f32 v0, v150, v95, -v187
	v_mul_f32_e32 v19, v19, v0
	v_fma_f32 v0, v150, v88, v188
	v_mul_f32_e32 v17, v17, v0
	v_fma_f32 v0, v150, v89, -v189
	v_mul_f32_e32 v20, v20, v0
	s_waitcnt lgkmcnt(5)
	v_fma_f32 v0, v150, v112, v190
	v_mul_f32_e32 v28, v29, v0
	v_fma_f32 v0, v150, v113, -v191
	v_mul_f32_e32 v12, v12, v0
	v_fma_f32 v0, v150, v104, v192
	v_mul_f32_e32 v22, v22, v0
	v_fma_f32 v0, v150, v105, -v193
	v_mul_f32_e32 v13, v13, v0
	s_waitcnt lgkmcnt(4)
	v_fma_f32 v0, v150, v96, v194
	v_mul_f32_e32 v29, v30, v0
	v_fma_f32 v0, v150, v97, -v195
	v_mul_f32_e32 v27, v27, v0
	v_fma_f32 v0, v150, v90, v196
	v_mul_f32_e32 v23, v23, v0
	v_fma_f32 v0, v150, v91, -v197
	v_mul_f32_e32 v30, v47, v0
	s_waitcnt lgkmcnt(3)
	v_fma_f32 v0, v150, v114, v198
	v_mul_f32_e32 v31, v31, v0
	v_fma_f32 v0, v150, v115, -v199
	v_mul_f32_e32 v47, v10, v0
	v_fma_f32 v0, v150, v106, v200
	v_mul_f32_e32 v10, v24, v0
	v_fma_f32 v0, v150, v107, -v201
	v_mul_f32_e32 v24, v11, v0
	s_waitcnt lgkmcnt(2)
	v_fma_f32 v0, v150, v98, v214
	v_mul_f32_e32 v11, v37, v0
	v_fma_f32 v0, v150, v99, -v215
	v_mul_f32_e32 v37, v81, v0
	v_fma_f32 v0, v150, v92, v216
	v_mul_f32_e32 v25, v25, v0
	v_fma_f32 v0, v150, v93, -v217
	v_mul_f32_e32 v81, v82, v0
	s_waitcnt lgkmcnt(1)
	v_fma_f32 v0, v150, v116, v218
	v_mul_f32_e32 v39, v39, v0
	v_fma_f32 v0, v150, v117, -v219
	v_mul_f32_e32 v82, v4, v0
	v_fma_f32 v0, v150, v108, v220
	v_mul_f32_e32 v26, v26, v0
	v_fma_f32 v0, v150, v109, -v221
	v_mul_f32_e32 v83, v5, v0
	s_waitcnt lgkmcnt(0)
	v_fma_f32 v0, v150, v100, v222
	v_mul_f32_e32 v8, v8, v0
	v_fma_f32 v0, v150, v101, -v223
	v_mul_f32_e32 v84, v6, v0
	v_fma_f32 v0, v150, v86, v224
	v_mul_f32_e32 v9, v9, v0
	v_fma_f32 v0, v150, v87, -v225
	v_mul_f32_e32 v85, v7, v0
	v_cvt_pk_bf16_f32 v0, v18, v16
	v_cvt_pk_bf16_f32 v1, v21, v17
	v_cvt_pk_bf16_f32 v2, v28, v22
	v_cvt_pk_bf16_f32 v3, v29, v23
	v_lshl_add_u64 v[16:17], v[78:79], 0, v[172:173]
	v_cvt_pk_bf16_f32 v4, v31, v10
	v_cvt_pk_bf16_f32 v5, v11, v25
	v_cvt_pk_bf16_f32 v6, v39, v26
	v_cvt_pk_bf16_f32 v7, v8, v9
	v_cvt_pk_bf16_f32 v8, v14, v15
	v_cvt_pk_bf16_f32 v9, v19, v20
	v_cvt_pk_bf16_f32 v10, v12, v13
	v_cvt_pk_bf16_f32 v11, v27, v30
	v_cvt_pk_bf16_f32 v12, v47, v24
	v_cvt_pk_bf16_f32 v13, v37, v81
	v_cvt_pk_bf16_f32 v14, v82, v83
	v_cvt_pk_bf16_f32 v15, v84, v85
	global_store_dwordx4 v[16:17], v[0:3], off
	global_store_dwordx4 v[16:17], v[4:7], off offset:16
	s_nop 0
	v_add_co_u32_e32 v2, vcc, 0xc0000, v16
	v_lshl_add_u64 v[0:1], v[16:17], 0, s[4:5]
	s_nop 0
	v_addc_co_u32_e32 v3, vcc, 0, v17, vcc
	global_store_dwordx4 v[2:3], v[8:11], off
	global_store_dwordx4 v[0:1], v[12:15], off offset:16

.LBB0_601:
	s_or_b64 exec, exec, s[4:5]
	s_waitcnt vmcnt(0)
	v_lshlrev_b32_e32 v21, 16, v157
	v_lshlrev_b32_e32 v19, 16, v158
	v_lshlrev_b32_e32 v20, 16, v159
	v_lshlrev_b32_e32 v18, 16, v160
	v_lshlrev_b32_e32 v16, 16, v12
	v_fma_f32 v21, v148, v21, v149
	v_and_b32_e32 v12, 0xffff0000, v12
	v_fmac_f32_e32 v21, v45, v16
	v_fma_f32 v16, v148, v16, v149
	v_lshlrev_b32_e32 v17, 16, v13
	v_fmac_f32_e32 v16, v45, v12
	v_fma_f32 v28, v148, v12, v149
	v_and_b32_e32 v13, 0xffff0000, v13
	v_fmac_f32_e32 v16, v44, v17
	v_fmac_f32_e32 v28, v45, v17
	v_fma_f32 v17, v148, v17, v149
	v_lshlrev_b32_e32 v22, 16, v14
	v_fmac_f32_e32 v17, v45, v13
	v_fma_f32 v29, v148, v13, v149
	v_and_b32_e32 v14, 0xffff0000, v14
	v_fmac_f32_e32 v17, v44, v22
	v_fmac_f32_e32 v29, v45, v22
	v_fma_f32 v22, v148, v22, v149
	v_lshlrev_b32_e32 v23, 16, v15
	v_fmac_f32_e32 v22, v45, v14
	v_fma_f32 v30, v148, v14, v149
	v_and_b32_e32 v15, 0xffff0000, v15
	v_fmac_f32_e32 v22, v44, v23
	v_fmac_f32_e32 v30, v45, v23
	v_fma_f32 v23, v148, v23, v149
	v_lshlrev_b32_e32 v24, 16, v8
	v_fmac_f32_e32 v23, v45, v15
	v_fma_f32 v31, v148, v15, v149
	v_and_b32_e32 v8, 0xffff0000, v8
	v_fmac_f32_e32 v23, v44, v24
	v_fmac_f32_e32 v31, v45, v24
	v_fma_f32 v24, v148, v24, v149
	v_lshlrev_b32_e32 v25, 16, v9
	v_fmac_f32_e32 v24, v45, v8
	v_fma_f32 v41, v148, v8, v149
	v_and_b32_e32 v9, 0xffff0000, v9
	v_fmac_f32_e32 v24, v44, v25
	v_fmac_f32_e32 v41, v45, v25
	v_fma_f32 v25, v148, v25, v149
	v_lshlrev_b32_e32 v26, 16, v10
	v_fmac_f32_e32 v25, v45, v9
	v_fma_f32 v58, v148, v9, v149
	v_and_b32_e32 v10, 0xffff0000, v10
	v_lshlrev_b32_e32 v27, 16, v11
	v_fmac_f32_e32 v25, v44, v26
	v_fmac_f32_e32 v58, v45, v26
	v_fma_f32 v26, v148, v26, v149
	v_and_b32_e32 v11, 0xffff0000, v11
	v_fmac_f32_e32 v31, v44, v8
	v_fmac_f32_e32 v41, v44, v9
	v_fmac_f32_e32 v58, v44, v10
	v_fmac_f32_e32 v26, v45, v10
	v_fma_f32 v8, v148, v10, v149
	v_fma_f32 v9, v148, v27, v149
	s_waitcnt vmcnt(0)
	v_and_b32_e32 v10, 0xffff0000, v4
	v_fmac_f32_e32 v21, v44, v12
	v_fmac_f32_e32 v28, v44, v13
	v_fmac_f32_e32 v9, v45, v11
	v_lshlrev_b32_e32 v13, 16, v4
	v_mov_b32_e32 v12, v10
	v_fmac_f32_e32 v29, v44, v14
	v_fmac_f32_e32 v30, v44, v15
	v_fmac_f32_e32 v8, v45, v27
	v_fmac_f32_e32 v9, v44, v19
	v_fma_f32 v19, v148, v20, v149
	v_pk_mul_f32 v[14:15], v[44:45], v[12:13]
	v_fmac_f32_e32 v8, v44, v11
	v_and_b32_e32 v11, 16, v4
	v_add_f32_e32 v4, v15, v19
	v_and_b32_e32 v12, 0xffff0000, v5
	v_add_f32_e32 v14, v14, v4
	v_fma_f32 v15, v148, v13, v149
	v_and_b32_e32 v13, 16, v5
	v_lshlrev_b32_e32 v5, 16, v5
	v_mov_b32_e32 v4, v12
	v_fma_f32 v19, v148, v10, v149
	v_pk_mov_b32 v[10:11], v[4:5], v[10:11] op_sel:[1,0]
	v_fmac_f32_e32 v26, v44, v27
	v_pk_mul_f32 v[10:11], v[44:45], v[10:11]
	v_fma_f32 v27, v148, v12, v149
	v_add_f32_e32 v11, v11, v15
	v_add_f32_e32 v15, v10, v11
	v_pk_mul_f32 v[10:11], v[44:45], v[4:5]
	v_fma_f32 v20, v148, v5, v149
	v_add_f32_e32 v4, v11, v19
	v_add_f32_e32 v19, v10, v4
	v_and_b32_e32 v4, 0xffff0000, v6
	v_lshlrev_b32_e32 v11, 16, v6
	v_mov_b32_e32 v10, v4
	v_pk_mov_b32 v[12:13], v[10:11], v[12:13] op_sel:[1,0]
	v_and_b32_e32 v5, 16, v6
	v_pk_mul_f32 v[12:13], v[44:45], v[12:13]
	s_mov_b64 s[4:5], 0xc00000
	v_add_f32_e32 v6, v13, v20
	v_add_f32_e32 v20, v12, v6
	v_pk_mul_f32 v[12:13], v[44:45], v[10:11]
	v_and_b32_e32 v10, 0xffff0000, v7
	v_add_f32_e32 v6, v13, v27
	v_add_f32_e32 v12, v12, v6
	v_fma_f32 v13, v148, v11, v149
	v_and_b32_e32 v11, 16, v7
	v_lshlrev_b32_e32 v7, 16, v7
	v_mov_b32_e32 v6, v10
	v_fma_f32 v27, v148, v4, v149
	v_pk_mov_b32 v[4:5], v[6:7], v[4:5] op_sel:[1,0]
	v_fma_f32 v59, v148, v7, v149
	v_pk_mul_f32 v[4:5], v[44:45], v[4:5]
	v_fma_f32 v60, v148, v10, v149
	v_add_f32_e32 v5, v5, v13
	v_add_f32_e32 v13, v4, v5
	v_pk_mul_f32 v[4:5], v[44:45], v[6:7]
	v_lshlrev_b32_e32 v7, 16, v0
	v_add_f32_e32 v5, v5, v27
	v_add_f32_e32 v27, v4, v5
	v_and_b32_e32 v4, 0xffff0000, v0
	v_mov_b32_e32 v6, v4
	v_pk_mov_b32 v[10:11], v[6:7], v[10:11] op_sel:[1,0]
	v_and_b32_e32 v5, 16, v0
	v_pk_mul_f32 v[10:11], v[44:45], v[10:11]
	s_nop 0
	v_add_f32_e32 v0, v11, v59
	v_add_f32_e32 v59, v10, v0
	v_pk_mul_f32 v[10:11], v[44:45], v[6:7]
	v_and_b32_e32 v6, 0xffff0000, v1
	v_add_f32_e32 v0, v60, v11
	v_add_f32_e32 v10, v10, v0
	v_fma_f32 v11, v148, v7, v149
	v_and_b32_e32 v7, 16, v1
	v_lshlrev_b32_e32 v1, 16, v1
	v_mov_b32_e32 v0, v6
	v_fma_f32 v60, v148, v4, v149
	v_pk_mov_b32 v[4:5], v[0:1], v[4:5] op_sel:[1,0]
	v_fma_f32 v94, v148, v6, v149
	v_pk_mul_f32 v[4:5], v[44:45], v[4:5]
	v_fma_f32 v61, v148, v1, v149
	v_add_f32_e32 v5, v5, v11
	v_add_f32_e32 v11, v4, v5
	v_pk_mul_f32 v[4:5], v[44:45], v[0:1]
	v_and_b32_e32 v1, 16, v2
	v_add_f32_e32 v0, v5, v60
	v_add_f32_e32 v60, v4, v0
	v_and_b32_e32 v0, 0xffff0000, v2
	v_lshlrev_b32_e32 v5, 16, v2
	v_mov_b32_e32 v4, v0
	v_pk_mov_b32 v[6:7], v[4:5], v[6:7] op_sel:[1,0]
	s_nop 0
	v_pk_mul_f32 v[6:7], v[44:45], v[6:7]
	s_nop 0
	v_add_f32_e32 v2, v7, v61
	v_add_f32_e32 v61, v6, v2
	v_pk_mul_f32 v[6:7], v[44:45], v[4:5]
	v_fma_f32 v5, v148, v5, v149
	v_add_f32_e32 v2, v7, v94
	v_add_f32_e32 v4, v6, v2
	v_and_b32_e32 v2, 0xffff0000, v3
	v_lshlrev_b32_e32 v3, 16, v3
	v_fma_f32 v6, v148, v0, v149
	v_pk_mov_b32 v[0:1], v[2:3], v[0:1] op_sel:[1,0]
	v_fma_f32 v7, v148, v3, v149
	v_pk_mul_f32 v[0:1], v[44:45], v[0:1]
	s_nop 0
	v_add_f32_e32 v1, v1, v5
	v_add_f32_e32 v5, v0, v1
	v_pk_mul_f32 v[0:1], v[44:45], v[2:3]
	v_mov_b32_e32 v3, v18
	v_add_f32_e32 v1, v1, v6
	v_add_f32_e32 v6, v0, v1
	v_pk_mul_f32 v[0:1], v[50:51], v[2:3]
	s_nop 0
	v_add_f32_e32 v0, v0, v7
	v_add_f32_e32 v7, v0, v1
	ds_read2_b64 v[182:185], v152 offset1:1
	ds_read2_b64 v[186:189], v152 offset0:2 offset1:3
	ds_read2_b64 v[190:193], v152 offset0:4 offset1:5
	ds_read2_b64 v[194:197], v152 offset0:6 offset1:7
	ds_read2_b64 v[198:201], v152 offset0:8 offset1:9
	ds_read2_b64 v[214:217], v152 offset0:10 offset1:11
	ds_read2_b64 v[218:221], v152 offset0:12 offset1:13
	ds_read2_b64 v[222:225], v152 offset0:14 offset1:15
	s_waitcnt lgkmcnt(7)
	v_fma_f32 v0, v150, v92, v182
	v_mul_f32_e32 v18, v21, v0
	v_fma_f32 v0, v150, v93, -v183
	v_mul_f32_e32 v14, v14, v0
	v_fma_f32 v0, v150, v86, v184
	v_mul_f32_e32 v16, v16, v0
	v_fma_f32 v0, v150, v87, -v185
	v_mul_f32_e32 v15, v15, v0
	s_waitcnt lgkmcnt(6)
	v_fma_f32 v0, v150, v76, v186
	v_mul_f32_e32 v21, v28, v0
	v_fma_f32 v0, v150, v77, -v187
	v_mul_f32_e32 v19, v19, v0
	v_fma_f32 v0, v150, v70, v188
	v_mul_f32_e32 v17, v17, v0
	v_fma_f32 v0, v150, v71, -v189
	v_mul_f32_e32 v20, v20, v0
	s_waitcnt lgkmcnt(5)
	v_fma_f32 v0, v150, v90, v190
	v_mul_f32_e32 v28, v29, v0
	v_fma_f32 v0, v150, v91, -v191
	v_mul_f32_e32 v12, v12, v0
	v_fma_f32 v0, v150, v82, v192
	v_mul_f32_e32 v22, v22, v0
	v_fma_f32 v0, v150, v83, -v193
	v_mul_f32_e32 v13, v13, v0
	s_waitcnt lgkmcnt(4)
	v_fma_f32 v0, v150, v74, v194
	v_mul_f32_e32 v29, v30, v0
	v_fma_f32 v0, v150, v75, -v195
	v_mul_f32_e32 v27, v27, v0
	v_fma_f32 v0, v150, v66, v196
	v_mul_f32_e32 v23, v23, v0
	v_fma_f32 v0, v150, v67, -v197
	v_mul_f32_e32 v30, v59, v0
	s_waitcnt lgkmcnt(3)
	v_fma_f32 v0, v150, v88, v198
	v_mul_f32_e32 v31, v31, v0
	v_fma_f32 v0, v150, v89, -v199
	v_mul_f32_e32 v59, v10, v0
	v_fma_f32 v0, v150, v80, v200
	v_mul_f32_e32 v10, v24, v0
	v_fma_f32 v0, v150, v81, -v201
	v_mul_f32_e32 v24, v11, v0
	s_waitcnt lgkmcnt(2)
	v_fma_f32 v0, v150, v72, v214
	v_mul_f32_e32 v11, v41, v0
	v_fma_f32 v0, v150, v73, -v215
	v_mul_f32_e32 v41, v60, v0
	v_fma_f32 v0, v150, v64, v216
	v_mul_f32_e32 v25, v25, v0
	v_fma_f32 v0, v150, v65, -v217
	v_mul_f32_e32 v60, v61, v0
	s_waitcnt lgkmcnt(1)
	v_fma_f32 v0, v150, v84, v218
	v_mul_f32_e32 v58, v58, v0
	v_fma_f32 v0, v150, v85, -v219
	v_mul_f32_e32 v61, v4, v0
	v_fma_f32 v0, v150, v78, v220
	v_mul_f32_e32 v26, v26, v0
	v_fma_f32 v0, v150, v79, -v221
	v_mul_f32_e32 v64, v5, v0
	s_waitcnt lgkmcnt(0)
	v_fma_f32 v0, v150, v68, v222
	v_mul_f32_e32 v8, v8, v0
	v_fma_f32 v0, v150, v69, -v223
	v_mul_f32_e32 v65, v6, v0
	v_fma_f32 v0, v150, v62, v224
	v_mul_f32_e32 v9, v9, v0
	v_fma_f32 v0, v150, v63, -v225
	v_mul_f32_e32 v62, v7, v0
	v_cvt_pk_bf16_f32 v0, v18, v16
	v_cvt_pk_bf16_f32 v1, v21, v17
	v_cvt_pk_bf16_f32 v2, v28, v22
	v_cvt_pk_bf16_f32 v3, v29, v23
	v_cvt_pk_bf16_f32 v4, v31, v10
	v_cvt_pk_bf16_f32 v5, v11, v25
	v_cvt_pk_bf16_f32 v6, v58, v26
	v_cvt_pk_bf16_f32 v7, v8, v9
	v_cvt_pk_bf16_f32 v8, v14, v15
	v_cvt_pk_bf16_f32 v9, v19, v20
	v_cvt_pk_bf16_f32 v10, v12, v13
	v_cvt_pk_bf16_f32 v11, v27, v30
	v_cvt_pk_bf16_f32 v12, v59, v24
	v_cvt_pk_bf16_f32 v13, v41, v60
	v_cvt_pk_bf16_f32 v14, v61, v64
	v_cvt_pk_bf16_f32 v15, v65, v62
	global_store_dwordx4 v[56:57], v[0:3], off
	global_store_dwordx4 v[56:57], v[4:7], off offset:16
	s_nop 0
	v_add_co_u32_e32 v2, vcc, 0xc00000, v56
	v_lshl_add_u64 v[0:1], v[56:57], 0, s[4:5]
	s_nop 0
	v_addc_co_u32_e32 v3, vcc, 0, v57, vcc
	global_store_dwordx4 v[2:3], v[8:11], off
	global_store_dwordx4 v[0:1], v[12:15], off offset:16

.LBB0_633:
	s_or_b64 exec, exec, s[28:29]
	v_mov_b32_e32 v86, 0
	v_mov_b32_e32 v92, 0
	v_mov_b32_e32 v93, 0
	s_and_saveexec_b64 s[4:5], s[40:41]
	s_cbranch_execz .LBB0_635
	ds_read_b64 v[182:183], v152
	ds_read_b64 v[184:185], v152 offset:8
	ds_read_b64 v[186:187], v152 offset:16
	ds_read_b64 v[188:189], v152 offset:24
	ds_read_b64 v[190:191], v152 offset:32
	ds_read_b64 v[192:193], v152 offset:40
	ds_read_b64 v[194:195], v152 offset:48
	ds_read_b64 v[196:197], v152 offset:56
	s_waitcnt lgkmcnt(7)
	v_pk_fma_f32 v[2:3], v[46:47], v[76:77], v[182:183]
	v_pk_fma_f32 v[0:1], v[46:47], v[76:77], v[182:183] neg_lo:[0,0,1] neg_hi:[0,0,1]
	s_nop 0
	v_mov_b32_e32 v3, v1
	v_pk_mul_f32 v[92:93], v[100:101], v[2:3]
.LBB0_635:
	s_or_b64 exec, exec, s[4:5]
	v_mov_b32_e32 v87, 0
	s_and_saveexec_b64 s[4:5], s[40:41]
	s_cbranch_execz .LBB0_637
	s_waitcnt lgkmcnt(6)
	v_pk_fma_f32 v[2:3], v[46:47], v[70:71], v[184:185]
	v_pk_fma_f32 v[0:1], v[46:47], v[70:71], v[184:185] neg_lo:[0,0,1] neg_hi:[0,0,1]
	s_nop 0
	v_mov_b32_e32 v3, v1
	v_pk_mul_f32 v[86:87], v[98:99], v[2:3]
.LBB0_637:
	s_or_b64 exec, exec, s[4:5]
	v_mov_b32_e32 v70, 0
	v_mov_b32_e32 v76, 0
	v_mov_b32_e32 v77, 0
	s_and_saveexec_b64 s[4:5], s[40:41]
	s_cbranch_execz .LBB0_639
	s_waitcnt lgkmcnt(5)
	v_pk_fma_f32 v[2:3], v[46:47], v[90:91], v[186:187]
	v_pk_fma_f32 v[0:1], v[46:47], v[90:91], v[186:187] neg_lo:[0,0,1] neg_hi:[0,0,1]
	s_nop 0
	v_mov_b32_e32 v3, v1
	v_pk_mul_f32 v[76:77], v[96:97], v[2:3]
.LBB0_639:
	s_or_b64 exec, exec, s[4:5]
	v_mov_b32_e32 v71, 0
	s_and_saveexec_b64 s[4:5], s[40:41]
	s_cbranch_execz .LBB0_641
	s_waitcnt lgkmcnt(4)
	v_pk_fma_f32 v[2:3], v[46:47], v[82:83], v[188:189]
	v_pk_fma_f32 v[0:1], v[46:47], v[82:83], v[188:189] neg_lo:[0,0,1] neg_hi:[0,0,1]
	s_nop 0
	v_mov_b32_e32 v3, v1
	v_pk_mul_f32 v[70:71], v[94:95], v[2:3]
.LBB0_641:
	s_or_b64 exec, exec, s[4:5]
	v_mov_b32_e32 v82, 0
	v_mov_b32_e32 v90, 0
	v_mov_b32_e32 v91, 0
	s_and_saveexec_b64 s[4:5], s[40:41]
	s_cbranch_execz .LBB0_643
	s_waitcnt lgkmcnt(3)
	v_pk_fma_f32 v[2:3], v[46:47], v[74:75], v[190:191]
	v_pk_fma_f32 v[0:1], v[46:47], v[74:75], v[190:191] neg_lo:[0,0,1] neg_hi:[0,0,1]
	s_nop 0
	v_mov_b32_e32 v3, v1
	v_pk_mul_f32 v[90:91], v[30:31], v[2:3]
.LBB0_643:
	s_or_b64 exec, exec, s[4:5]
	v_mov_b32_e32 v83, 0
	s_and_saveexec_b64 s[4:5], s[40:41]
	s_cbranch_execz .LBB0_645
	s_waitcnt lgkmcnt(2)
	v_pk_fma_f32 v[2:3], v[46:47], v[66:67], v[192:193]
	v_pk_fma_f32 v[0:1], v[46:47], v[66:67], v[192:193] neg_lo:[0,0,1] neg_hi:[0,0,1]
	s_nop 0
	v_mov_b32_e32 v3, v1
	v_pk_mul_f32 v[82:83], v[28:29], v[2:3]
.LBB0_645:
	s_or_b64 exec, exec, s[4:5]
	v_mov_b32_e32 v66, 0
	v_mov_b32_e32 v74, 0
	v_mov_b32_e32 v75, 0
	s_and_saveexec_b64 s[4:5], s[40:41]
	s_cbranch_execz .LBB0_647
	s_waitcnt lgkmcnt(1)
	v_pk_fma_f32 v[2:3], v[46:47], v[88:89], v[194:195]
	v_pk_fma_f32 v[0:1], v[46:47], v[88:89], v[194:195] neg_lo:[0,0,1] neg_hi:[0,0,1]
	s_nop 0
	v_mov_b32_e32 v3, v1
	v_pk_mul_f32 v[74:75], v[26:27], v[2:3]
.LBB0_647:
	s_or_b64 exec, exec, s[4:5]
	v_mov_b32_e32 v67, 0
	s_and_saveexec_b64 s[4:5], s[40:41]
	s_cbranch_execz .LBB0_649
	s_waitcnt lgkmcnt(0)
	v_pk_fma_f32 v[2:3], v[46:47], v[80:81], v[196:197]
	v_pk_fma_f32 v[0:1], v[46:47], v[80:81], v[196:197] neg_lo:[0,0,1] neg_hi:[0,0,1]
	s_nop 0
	v_mov_b32_e32 v3, v1
	v_pk_mul_f32 v[66:67], v[24:25], v[2:3]
.LBB0_649:
	s_or_b64 exec, exec, s[4:5]
	v_mov_b32_e32 v80, 0
	v_mov_b32_e32 v88, 0
	v_mov_b32_e32 v89, 0
	s_and_saveexec_b64 s[4:5], s[40:41]
	s_cbranch_execz .LBB0_651
	ds_read_b64 v[198:199], v152 offset:64
	ds_read_b64 v[200:201], v152 offset:72
	ds_read_b64 v[202:203], v152 offset:80
	ds_read_b64 v[214:215], v152 offset:88
	ds_read_b64 v[216:217], v152 offset:96
	ds_read_b64 v[218:219], v152 offset:104
	ds_read_b64 v[220:221], v152 offset:112
	ds_read_b64 v[222:223], v152 offset:120
	s_waitcnt lgkmcnt(7)
	v_pk_fma_f32 v[2:3], v[46:47], v[72:73], v[198:199]
	v_pk_fma_f32 v[0:1], v[46:47], v[72:73], v[198:199] neg_lo:[0,0,1] neg_hi:[0,0,1]
	s_nop 0
	v_mov_b32_e32 v3, v1
	v_pk_mul_f32 v[88:89], v[22:23], v[2:3]
.LBB0_651:
	s_or_b64 exec, exec, s[4:5]
	v_mov_b32_e32 v81, 0
	s_and_saveexec_b64 s[4:5], s[40:41]
	s_cbranch_execz .LBB0_653
	s_waitcnt lgkmcnt(6)
	v_pk_fma_f32 v[2:3], v[46:47], v[64:65], v[200:201]
	v_pk_fma_f32 v[0:1], v[46:47], v[64:65], v[200:201] neg_lo:[0,0,1] neg_hi:[0,0,1]
	s_nop 0
	v_mov_b32_e32 v3, v1
	v_pk_mul_f32 v[80:81], v[20:21], v[2:3]
.LBB0_653:
	s_or_b64 exec, exec, s[4:5]
	v_mov_b32_e32 v64, 0
	v_mov_b32_e32 v72, 0
	v_mov_b32_e32 v73, 0
	s_and_saveexec_b64 s[4:5], s[40:41]
	s_cbranch_execz .LBB0_655
	s_waitcnt lgkmcnt(5)
	v_pk_fma_f32 v[2:3], v[46:47], v[84:85], v[202:203]
	v_pk_fma_f32 v[0:1], v[46:47], v[84:85], v[202:203] neg_lo:[0,0,1] neg_hi:[0,0,1]
	s_nop 0
	v_mov_b32_e32 v3, v1
	v_pk_mul_f32 v[72:73], v[18:19], v[2:3]
.LBB0_655:
	s_or_b64 exec, exec, s[4:5]
	v_mov_b32_e32 v65, 0
	s_and_saveexec_b64 s[4:5], s[40:41]
	s_cbranch_execz .LBB0_657
	s_waitcnt lgkmcnt(4)
	v_pk_fma_f32 v[2:3], v[46:47], v[78:79], v[214:215]
	v_pk_fma_f32 v[0:1], v[46:47], v[78:79], v[214:215] neg_lo:[0,0,1] neg_hi:[0,0,1]
	s_nop 0
	v_mov_b32_e32 v3, v1
	v_pk_mul_f32 v[64:65], v[16:17], v[2:3]
.LBB0_657:
	s_or_b64 exec, exec, s[4:5]
	v_mov_b32_e32 v78, 0
	v_mov_b32_e32 v84, 0
	v_mov_b32_e32 v85, 0
	s_and_saveexec_b64 s[4:5], s[40:41]
	s_cbranch_execz .LBB0_659
	s_waitcnt lgkmcnt(3)
	v_pk_fma_f32 v[2:3], v[46:47], v[68:69], v[216:217]
	v_pk_fma_f32 v[0:1], v[46:47], v[68:69], v[216:217] neg_lo:[0,0,1] neg_hi:[0,0,1]
	s_nop 0
	v_mov_b32_e32 v3, v1
	v_pk_mul_f32 v[84:85], v[14:15], v[2:3]
.LBB0_659:
	s_or_b64 exec, exec, s[4:5]
	v_mov_b32_e32 v79, 0
	s_and_saveexec_b64 s[4:5], s[40:41]
	s_cbranch_execz .LBB0_661
	s_waitcnt lgkmcnt(2)
	v_pk_fma_f32 v[2:3], v[46:47], v[62:63], v[218:219]
	v_pk_fma_f32 v[0:1], v[46:47], v[62:63], v[218:219] neg_lo:[0,0,1] neg_hi:[0,0,1]
	s_nop 0
	v_mov_b32_e32 v3, v1
	v_pk_mul_f32 v[78:79], v[12:13], v[2:3]
.LBB0_661:
	s_or_b64 exec, exec, s[4:5]
	v_mov_b32_e32 v62, 0
	v_mov_b32_e32 v68, 0
	v_mov_b32_e32 v69, 0
	s_and_saveexec_b64 s[4:5], s[40:41]
	s_cbranch_execz .LBB0_663
	s_waitcnt lgkmcnt(1)
	v_pk_fma_f32 v[2:3], v[46:47], v[60:61], v[220:221]
	v_pk_fma_f32 v[0:1], v[46:47], v[60:61], v[220:221] neg_lo:[0,0,1] neg_hi:[0,0,1]
	s_nop 0
	v_mov_b32_e32 v3, v1
	v_pk_mul_f32 v[68:69], v[10:11], v[2:3]
.LBB0_663:
	s_or_b64 exec, exec, s[4:5]
	v_mov_b32_e32 v63, 0
	s_and_saveexec_b64 s[4:5], s[40:41]
	s_cbranch_execz .LBB0_665
	s_waitcnt lgkmcnt(0)
	v_pk_fma_f32 v[2:3], v[46:47], v[58:59], v[222:223]
	v_pk_fma_f32 v[0:1], v[46:47], v[58:59], v[222:223] neg_lo:[0,0,1] neg_hi:[0,0,1]
	s_nop 0
	v_mov_b32_e32 v3, v1
	v_pk_mul_f32 v[62:63], v[8:9], v[2:3]
